# plus: cooperative-groups grid.sync after phase 0 replaced by a copy of the kernel's XCD-hierarchical barrier
# speedup vs baseline: 1.0260x; 1.0105x over previous
;   DI bf16_t* z() const { return (bf16_t*)(ws + OFF_Z); }
;   DI unsigned* bar() const { return (unsigned*)(ws + OFF_BAR); }
; __device__ __forceinline__ unsigned xb_ld(unsigned* p)              { return __hip_atomic_load(p, __ATOMIC_RELAXED, __HIP_MEMORY_SCOPE_AGENT); }
; __device__ __forceinline__ void xcd_barrier_complete(unsigned* bar, unsigned x, unsigned& nloc, unsigned& nx) {
;     const unsigned G = gridDim.x * gridDim.y * gridDim.z;
;     unsigned sum, cnt, mine, sp = 0u;
;     for (;;) {
;         sum = 0u; cnt = 0u; mine = 0u;
; #pragma unroll
;         for (unsigned j = 0; j < 16; ++j) { const unsigned c = xb_ld(&bar[XB_XCNT(j)]); sum += c; cnt += (c > 0u) ? 1u : 0u; mine = (j == x) ? c : mine; }
;         if (sum == G) break;
;         __builtin_amdgcn_s_sleep(1);
;         if ((++sp & 255u) == 0u) { if (xb_ld(&bar[XB_TMO])) break; if (sp > XB_SPIN_CAP) { atomicAdd(&bar[XB_TMO], 1u); break; } }
; __device__ __forceinline__ void xcd_barrier(const XcdBarrier& b) {
;     asm volatile("s_waitcnt vmcnt(0)" ::: "memory");
;     __syncthreads();
;     if (threadIdx.x == 0) {
;         unsigned* bar = b.bar;
;         __builtin_amdgcn_s_waitcnt(0);
;         unsigned nloc = b.st[0], nx = b.st[1];
;         if (nloc == 0u) { xcd_barrier_complete(bar, b.x, nloc, nx); b.st[0] = nloc; b.st[1] = nx; }
.LBB0_84:
	s_or_b64 exec, exec, s[0:1]
	s_waitcnt vmcnt(0)
	s_barrier
	s_mov_b64 s[0:1], exec
	v_readlane_b32 s2, v252, 2
	v_readlane_b32 s3, v252, 3
	s_and_b64 s[2:3], s[0:1], s[2:3]
	s_mov_b64 exec, s[2:3]
	s_cbranch_execz .Lgs_185
	v_mov_b32_e32 v0, 0
	s_waitcnt vmcnt(0) expcnt(0) lgkmcnt(0)
	ds_read_b32 v2, v0
	ds_read_b32 v1, v0 offset:4
	s_waitcnt lgkmcnt(1)
	v_cmp_ne_u32_e32 vcc, 0, v2
	s_cbranch_vccnz .Lgs_149
	v_readlane_b32 s2, v252, 0
	s_mul_i32 s33, s97, s2
	s_add_u32 s2, s22, 0x1e6c1200
	s_addc_u32 s3, s23, 0
	s_add_u32 s4, s22, 0x1e6c1400
	s_addc_u32 s5, s23, 0
	s_add_u32 s6, s22, 0x1e6c1500
	s_addc_u32 s7, s23, 0
	s_add_u32 s8, s22, 0x1e6c1600
	s_addc_u32 s9, s23, 0
	s_add_u32 s10, s22, 0x1e6c1700
	s_addc_u32 s11, s23, 0
	s_add_u32 s12, s22, 0x1e6c1800
	s_addc_u32 s13, s23, 0
	s_add_u32 s14, s22, 0x1e6c1900
	s_addc_u32 s15, s23, 0
	s_add_u32 s16, s22, 0x1e6c1a00
	s_addc_u32 s17, s23, 0
	s_add_u32 s18, s22, 0x1e6c1b00
	s_addc_u32 s19, s23, 0
	s_add_u32 s24, s22, 0x1e6c1c00
	s_addc_u32 s25, s23, 0
	s_add_u32 s26, s22, 0x1e6c1d00
	s_addc_u32 s27, s23, 0
	s_add_u32 s28, s22, 0x1e6c1e00
	s_addc_u32 s29, s23, 0
	s_add_u32 s30, s22, 0x1e6c1f00
	s_addc_u32 s31, s23, 0
	s_add_u32 s34, s22, 0x1e6c2000
	s_addc_u32 s35, s23, 0
	s_add_u32 s36, s22, 0x1e6c2100
	s_addc_u32 s37, s23, 0
	s_add_u32 s38, s22, 0x1e6c2200
	s_addc_u32 s39, s23, 0
	s_add_u32 s40, s22, 0x1e6c2300
	s_mul_i32 s33, s33, s96
	s_addc_u32 s41, s23, 0
	s_mov_b32 s48, 1
	s_branch .Lgs_137

;   DI bf16_t* wt_in0() const { return (bf16_t*)(ws + OFF_WT_IN0); }
;   DI bf16_t* h() const { return (bf16_t*)(ws + OFF_H); }
; DI void phase_gemm_in0(const Params& p, char* smem) {
;   u32x4 ra[4], rb[4]; bool pre = false;
;   for (int t = blockIdx.x; t < 64 * 16; t += gridDim.x) {
;     const int mt = t & 63, nt = t >> 6, tn = t + gridDim.x;
;     const bool has_next = tn < 64 * 16;
;     const GTile tl{p.h(), D, p.wt_in0(), D, D, mt * 256, nt * 256}, nx{p.h(), D, p.wt_in0(), D, D, (tn & 63) * 256, (tn >> 6) * 256};
; __device__ __forceinline__ void xcd_barrier(const XcdBarrier& b) {
;     ...
;     }
;     __syncthreads();
; }
.Lgs_185:
	s_or_b64 exec, exec, s[0:1]
	s_cmpk_lt_i32 s84, 0x400
	s_cselect_b64 s[0:1], -1, 0
	v_writelane_b32 v252, s0, 39
	s_cmpk_gt_i32 s84, 0x3ff
	s_waitcnt lgkmcnt(0)
	s_barrier
	v_writelane_b32 v252, s1, 40
	s_cbranch_scc1 .LBB0_129
	s_add_u32 s16, s22, 0x40c0000
	s_addc_u32 s17, s23, 0
	s_add_u32 s6, s22, 0xc00000
	s_addc_u32 s7, s23, 0
	s_add_u32 s8, s22, 0xc00080
	s_addc_u32 s9, s23, 0
	s_add_u32 s10, s22, 0xc40080
	s_addc_u32 s11, s23, 0
	s_add_u32 s12, s22, 0xc80080
	s_addc_u32 s13, s23, 0
	s_add_u32 s14, s22, 0xcc0080
	s_addc_u32 s15, s23, 0
	s_add_u32 s26, s22, 0xc40000
	s_addc_u32 s27, s23, 0
	s_add_u32 s28, s22, 0xc80000
	s_addc_u32 s29, s23, 0
	s_add_u32 s30, s22, 0x150c0000
	s_addc_u32 s31, s23, 0
	s_add_u32 s18, s22, 0x80c0000
	s_addc_u32 s19, s23, 0
	s_add_i32 s0, s84, s96
	s_lshl_b32 s24, s84, 8
	s_lshl_b32 s25, s96, 8
	s_lshl_b32 s36, s0, 19
	s_lshl_b32 s37, s96, 19
	s_lshl_b32 s38, s0, 2
	s_lshl_b32 s39, s96, 2
	s_mov_b64 s[0:1], 0
	v_mov_b32_e32 v193, 0
	s_mov_b32 s40, 0x40000
	s_mov_b32 s41, 0x80000
	s_mov_b32 s44, 0xc0000
	s_movk_i32 s45, 0x90
	s_mov_b64 s[34:35], 0x40000
	s_mov_b64 s[42:43], 0x80000
	s_movk_i32 s46, 0x2200
	s_mov_b32 s47, s84
	s_branch .LBB0_98
